# attn64: tile-range test on SGPRs; first V-fragment group read issued before the between-block checks into spare VGPRs
# speedup vs baseline: 1.0130x; 1.0023x over previous
.LBB0_940:
	s_add_i32 s6, s80, 0xffffe000
	s_and_b32 s6, s6, 0x6000
	s_add_i32 s6, s6, 0
	s_add_i32 s6, s6, 0x14000
	v_add_u32_e32 v3, s6, v206
	v_add_u32_e32 v8, s6, v210
	ds_read_b128 v[4:7], v3
	ds_read_b128 v[8:11], v8 offset:4096
	s_waitcnt lgkmcnt(1)
	v_mfma_f32_32x32x16_bf16 v[132:147], v[4:7], v[176:179], v[82:97]
	v_add_u32_e32 v3, s6, v207
	ds_read_b128 v[12:15], v3
	v_add_u32_e32 v3, s6, v211
	ds_read_b128 v[216:219], v3 offset:4096
	v_add_f32_e32 v3, 0, v100
	v_add_f32_e32 v3, v101, v3
	v_add_f32_e32 v3, v102, v3
	v_add_f32_e32 v3, v103, v3
	v_cvt_pk_bf16_f32 v180, v100, v101
	v_cvt_pk_bf16_f32 v181, v102, v103
	s_waitcnt lgkmcnt(2)
	v_mfma_f32_32x32x16_bf16 v[148:163], v[8:11], v[176:179], v[82:97]
	v_add_f32_e32 v3, v104, v3
	v_add_f32_e32 v3, v105, v3
	v_add_f32_e32 v3, v106, v3
	v_add_f32_e32 v3, v107, v3
	v_cvt_pk_bf16_f32 v182, v104, v105
	v_cvt_pk_bf16_f32 v183, v106, v107
	s_waitcnt lgkmcnt(1)
	v_mfma_f32_32x32x16_bf16 v[132:147], v[12:15], v[172:175], v[132:147]
	v_add_u32_e32 v4, s6, v208
	v_add_u32_e32 v8, s6, v212
	ds_read_b128 v[4:7], v4
	ds_read_b128 v[220:223], v8 offset:4096
	v_add_f32_e32 v3, v108, v3
	v_add_f32_e32 v3, v109, v3
	v_add_f32_e32 v3, v110, v3
	v_add_f32_e32 v3, v111, v3
	v_cvt_pk_bf16_f32 v12, v108, v109
	v_cvt_pk_bf16_f32 v13, v110, v111
	s_waitcnt lgkmcnt(2)
	v_mfma_f32_32x32x16_bf16 v[148:163], v[216:219], v[172:175], v[148:163]
	v_add_f32_e32 v3, v112, v3
	v_add_f32_e32 v3, v113, v3
	v_add_f32_e32 v3, v114, v3
	v_add_f32_e32 v3, v115, v3
	v_cvt_pk_bf16_f32 v14, v112, v113
	v_cvt_pk_bf16_f32 v15, v114, v115
	s_waitcnt lgkmcnt(1)
	v_mfma_f32_32x32x16_bf16 v[132:147], v[4:7], v[168:171], v[132:147]
	v_add_u32_e32 v8, s6, v209
	v_add_u32_e32 v9, s6, v213
	ds_read_b128 v[216:219], v8
	ds_read_b128 v[224:227], v9 offset:4096
	v_add_f32_e32 v3, v116, v3
	v_add_f32_e32 v3, v117, v3
	v_add_f32_e32 v3, v118, v3
	v_add_f32_e32 v3, v119, v3
	v_cvt_pk_bf16_f32 v8, v116, v117
	v_cvt_pk_bf16_f32 v9, v118, v119
	s_waitcnt lgkmcnt(2)
	v_mfma_f32_32x32x16_bf16 v[148:163], v[220:223], v[168:171], v[148:163]
	v_add_f32_e32 v3, v120, v3
	v_add_f32_e32 v3, v121, v3
	v_add_f32_e32 v3, v122, v3
	v_add_f32_e32 v3, v123, v3
	v_cvt_pk_bf16_f32 v10, v120, v121
	v_cvt_pk_bf16_f32 v11, v122, v123
	s_waitcnt lgkmcnt(1)
	v_mfma_f32_32x32x16_bf16 v[132:147], v[216:219], v[164:167], v[132:147]
	v_add_f32_e32 v3, v124, v3
	v_add_f32_e32 v3, v125, v3
	v_add_f32_e32 v3, v126, v3
	v_add_f32_e32 v3, v127, v3
	v_cvt_pk_bf16_f32 v4, v124, v125
	v_cvt_pk_bf16_f32 v5, v126, v127
	s_waitcnt lgkmcnt(0)
	v_mfma_f32_32x32x16_bf16 v[148:163], v[224:227], v[164:167], v[148:163]
	v_add_f32_e32 v3, v128, v3
	v_add_f32_e32 v3, v129, v3
	v_add_f32_e32 v3, v130, v3
	v_add_f32_e32 v3, v131, v3
	v_cvt_pk_bf16_f32 v6, v128, v129
	v_cvt_pk_bf16_f32 v7, v130, v131
	s_mul_hi_u32 s6, s81, 0xcccccccd
	s_lshr_b32 s6, s6, 2
	s_mul_i32 s6, s6, 0x14000
	v_subrev_u32_e32 v243, s6, v215
	ds_read_b64_tr_b16 v[228:229], v243 offset:0
	ds_read_b64_tr_b16 v[230:231], v243 offset:0x800
	ds_read_b64_tr_b16 v[232:233], v243 offset:0x200
	ds_read_b64_tr_b16 v[234:235], v243 offset:0xa00
	ds_read_b64_tr_b16 v[236:237], v243 offset:0x400
	ds_read_b64_tr_b16 v[238:239], v243 offset:0xc00
	ds_read_b64_tr_b16 v[240:241], v243 offset:0x600
	ds_read_b64_tr_b16 v[242:243], v243 offset:0xe00
	s_nop 0
	v_cmp_ge_f32_e32 vcc, s38, v3
	s_cmp_eq_u64 vcc, exec
	s_cbranch_scc0 .LBB0_958
.LBB0_941:
	s_add_i32 s6, s84, -1
	s_cmp_le_i32 s6, s35
	s_cbranch_scc0 .LBB0_959

.LBB0_946:
	s_mul_hi_u32 s6, s81, 0xcccccccd
	s_lshr_b32 s6, s6, 2
	s_mul_i32 s6, s6, 0x14000
	v_subrev_u32_e32 v16, s6, v215
	s_cmp_lg_u32 0, -1
	s_cselect_b32 s6, 0, 0
	v_add_u32_e32 v16, s6, v16
	ds_read_b64_tr_b16 v[116:117], v16 offset:0x1000
	ds_read_b64_tr_b16 v[118:119], v16 offset:0x1800
	ds_read_b64_tr_b16 v[120:121], v16 offset:0x1200
	ds_read_b64_tr_b16 v[122:123], v16 offset:0x1a00
	ds_read_b64_tr_b16 v[124:125], v16 offset:0x1400
	ds_read_b64_tr_b16 v[126:127], v16 offset:0x1c00
	ds_read_b64_tr_b16 v[128:129], v16 offset:0x1600
	ds_read_b64_tr_b16 v[130:131], v16 offset:0x1e00
	s_waitcnt lgkmcnt(8)
	s_nop 0
	v_mfma_f32_32x32x16_bf16 v[66:81], v[228:231], v[180:183], v[66:81]
	v_exp_f32_e32 v132, v132
	v_exp_f32_e32 v133, v133
	v_mfma_f32_32x32x16_bf16 v[50:65], v[232:235], v[180:183], v[50:65]
	v_exp_f32_e32 v134, v134
	v_exp_f32_e32 v135, v135
	v_mfma_f32_32x32x16_bf16 v[34:49], v[236:239], v[180:183], v[34:49]
	v_exp_f32_e32 v136, v136
	v_exp_f32_e32 v137, v137
	v_mfma_f32_32x32x16_bf16 v[18:33], v[240:243], v[180:183], v[18:33]
	v_exp_f32_e32 v138, v138
	v_exp_f32_e32 v139, v139
	ds_read_b64_tr_b16 v[100:101], v16 offset:0x2000
	ds_read_b64_tr_b16 v[102:103], v16 offset:0x2800
	ds_read_b64_tr_b16 v[104:105], v16 offset:0x2200
	ds_read_b64_tr_b16 v[106:107], v16 offset:0x2a00
	ds_read_b64_tr_b16 v[108:109], v16 offset:0x2400
	ds_read_b64_tr_b16 v[110:111], v16 offset:0x2c00
	ds_read_b64_tr_b16 v[112:113], v16 offset:0x2600
	ds_read_b64_tr_b16 v[114:115], v16 offset:0x2e00
	s_waitcnt lgkmcnt(8)
	v_mfma_f32_32x32x16_bf16 v[66:81], v[116:119], v[12:15], v[66:81]
	v_exp_f32_e32 v140, v140
	v_exp_f32_e32 v141, v141
	v_mfma_f32_32x32x16_bf16 v[50:65], v[120:123], v[12:15], v[50:65]
	v_exp_f32_e32 v142, v142
	v_exp_f32_e32 v143, v143
	v_mfma_f32_32x32x16_bf16 v[34:49], v[124:127], v[12:15], v[34:49]
	v_exp_f32_e32 v144, v144
	v_exp_f32_e32 v145, v145
	v_mfma_f32_32x32x16_bf16 v[18:33], v[128:131], v[12:15], v[18:33]
	v_exp_f32_e32 v146, v146
	v_exp_f32_e32 v147, v147
	ds_read_b64_tr_b16 v[12:13], v16 offset:0x3000
	ds_read_b64_tr_b16 v[14:15], v16 offset:0x3800
	ds_read_b64_tr_b16 v[116:117], v16 offset:0x3200
	ds_read_b64_tr_b16 v[118:119], v16 offset:0x3a00
	ds_read_b64_tr_b16 v[120:121], v16 offset:0x3400
	ds_read_b64_tr_b16 v[122:123], v16 offset:0x3c00
	ds_read_b64_tr_b16 v[124:125], v16 offset:0x3600
	ds_read_b64_tr_b16 v[126:127], v16 offset:0x3e00
	s_waitcnt lgkmcnt(8)
	v_mfma_f32_32x32x16_bf16 v[66:81], v[100:103], v[8:11], v[66:81]
	v_exp_f32_e32 v148, v148
	v_exp_f32_e32 v149, v149
	v_mfma_f32_32x32x16_bf16 v[50:65], v[104:107], v[8:11], v[50:65]
	v_exp_f32_e32 v150, v150
	v_exp_f32_e32 v151, v151
	v_mfma_f32_32x32x16_bf16 v[34:49], v[108:111], v[8:11], v[34:49]
	v_exp_f32_e32 v152, v152
	v_exp_f32_e32 v153, v153
	v_mfma_f32_32x32x16_bf16 v[18:33], v[112:115], v[8:11], v[18:33]
	v_exp_f32_e32 v154, v154
	v_exp_f32_e32 v155, v155
	s_waitcnt lgkmcnt(0)
	v_mfma_f32_32x32x16_bf16 v[66:81], v[12:15], v[4:7], v[66:81]
	v_exp_f32_e32 v156, v156
	v_exp_f32_e32 v157, v157
	v_mfma_f32_32x32x16_bf16 v[50:65], v[116:119], v[4:7], v[50:65]
	v_exp_f32_e32 v158, v158
	v_exp_f32_e32 v159, v159
	v_mfma_f32_32x32x16_bf16 v[34:49], v[120:123], v[4:7], v[34:49]
	v_exp_f32_e32 v160, v160
	v_exp_f32_e32 v161, v161
	v_mfma_f32_32x32x16_bf16 v[18:33], v[124:127], v[4:7], v[18:33]
	v_exp_f32_e32 v162, v162
	v_exp_f32_e32 v163, v163
	s_add_i32 s83, s84, 2
	s_cmp_ge_u32 s83, s50
	s_cselect_b64 s[68:69], -1, 0
	s_and_b64 vcc, exec, s[68:69]
	s_cbranch_vccnz .LBB0_948
	s_mul_hi_u32 s6, s13, 0xcccccccd
	s_lshr_b32 s6, s6, 2
	s_mul_i32 s6, s6, 0x14000
	s_sub_i32 s17, s14, s6
	s_min_i32 s6, s83, s49
	s_lshl_b64 s[18:19], s[6:7], 17
	s_add_u32 s20, s52, s18
	s_addc_u32 s21, s53, s19
	s_add_u32 s18, s66, s18
	s_addc_u32 s19, s67, s19
	s_cmp_lg_u32 0, -1
	s_cselect_b32 s6, 0, 0
	s_add_i32 s6, s17, s6
	s_add_i32 s17, s80, 0x4000
	s_and_b32 s17, s17, 0x6000
	s_add_i32 s17, s17, s11
	s_mov_b32 s22, m0
	s_mov_b32 m0, s6
	s_nop 0
	global_load_lds_dwordx4 v194, s[20:21]
	s_mov_b32 m0, s22
	s_add_u32 s20, s20, 0x10000
	s_addc_u32 s21, s21, 0
	s_addk_i32 s6, 0x2000
	s_mov_b32 s22, m0
	s_mov_b32 m0, s6
	s_nop 0
	global_load_lds_dwordx4 v194, s[20:21]
	s_mov_b32 m0, s22
	s_mov_b32 s6, m0
	s_mov_b32 m0, s17
	s_nop 0
	global_load_lds_dwordx4 v195, s[18:19]
	s_mov_b32 m0, s6

.LBB0_950:
	v_add_f32_e32 v16, v3, v184
	s_and_b32 s17, s80, 0x6000
	s_add_i32 s17, s17, 0
	s_add_i32 s17, s17, 0x14000
	v_add_u32_e32 v3, s17, v206
	v_add_u32_e32 v8, s17, v210
	ds_read_b128 v[4:7], v3
	ds_read_b128 v[8:11], v8 offset:4096
	s_waitcnt lgkmcnt(1)
	v_mfma_f32_32x32x16_bf16 v[100:115], v[4:7], v[176:179], v[82:97]
	v_add_u32_e32 v3, s17, v207
	ds_read_b128 v[12:15], v3
	v_add_u32_e32 v3, s17, v211
	ds_read_b128 v[216:219], v3 offset:4096
	v_add_f32_e32 v3, 0, v132
	v_add_f32_e32 v3, v133, v3
	v_add_f32_e32 v3, v134, v3
	v_add_f32_e32 v3, v135, v3
	v_cvt_pk_bf16_f32 v180, v132, v133
	v_cvt_pk_bf16_f32 v181, v134, v135
	s_waitcnt lgkmcnt(2)
	v_mfma_f32_32x32x16_bf16 v[116:131], v[8:11], v[176:179], v[82:97]
	v_add_f32_e32 v3, v136, v3
	v_add_f32_e32 v3, v137, v3
	v_add_f32_e32 v3, v138, v3
	v_add_f32_e32 v3, v139, v3
	v_cvt_pk_bf16_f32 v182, v136, v137
	v_cvt_pk_bf16_f32 v183, v138, v139
	s_waitcnt lgkmcnt(1)
	v_mfma_f32_32x32x16_bf16 v[100:115], v[12:15], v[172:175], v[100:115]
	v_add_u32_e32 v4, s17, v208
	v_add_u32_e32 v8, s17, v212
	ds_read_b128 v[4:7], v4
	ds_read_b128 v[220:223], v8 offset:4096
	v_add_f32_e32 v3, v140, v3
	v_add_f32_e32 v3, v141, v3
	v_add_f32_e32 v3, v142, v3
	v_add_f32_e32 v3, v143, v3
	v_cvt_pk_bf16_f32 v12, v140, v141
	v_cvt_pk_bf16_f32 v13, v142, v143
	s_waitcnt lgkmcnt(2)
	v_mfma_f32_32x32x16_bf16 v[116:131], v[216:219], v[172:175], v[116:131]
	v_add_f32_e32 v3, v144, v3
	v_add_f32_e32 v3, v145, v3
	v_add_f32_e32 v3, v146, v3
	v_add_f32_e32 v3, v147, v3
	v_cvt_pk_bf16_f32 v14, v144, v145
	v_cvt_pk_bf16_f32 v15, v146, v147
	s_waitcnt lgkmcnt(1)
	v_mfma_f32_32x32x16_bf16 v[100:115], v[4:7], v[168:171], v[100:115]
	v_add_u32_e32 v8, s17, v209
	v_add_u32_e32 v9, s17, v213
	ds_read_b128 v[216:219], v8
	ds_read_b128 v[224:227], v9 offset:4096
	v_add_f32_e32 v3, v148, v3
	v_add_f32_e32 v3, v149, v3
	v_add_f32_e32 v3, v150, v3
	v_add_f32_e32 v3, v151, v3
	v_cvt_pk_bf16_f32 v8, v148, v149
	v_cvt_pk_bf16_f32 v9, v150, v151
	s_waitcnt lgkmcnt(2)
	v_mfma_f32_32x32x16_bf16 v[116:131], v[220:223], v[168:171], v[116:131]
	v_add_f32_e32 v3, v152, v3
	v_add_f32_e32 v3, v153, v3
	v_add_f32_e32 v3, v154, v3
	v_add_f32_e32 v3, v155, v3
	v_cvt_pk_bf16_f32 v10, v152, v153
	v_cvt_pk_bf16_f32 v11, v154, v155
	s_waitcnt lgkmcnt(1)
	v_mfma_f32_32x32x16_bf16 v[100:115], v[216:219], v[164:167], v[100:115]
	v_add_f32_e32 v3, v156, v3
	v_add_f32_e32 v3, v157, v3
	v_add_f32_e32 v3, v158, v3
	v_add_f32_e32 v3, v159, v3
	v_cvt_pk_bf16_f32 v4, v156, v157
	v_cvt_pk_bf16_f32 v5, v158, v159
	s_waitcnt lgkmcnt(0)
	v_mfma_f32_32x32x16_bf16 v[116:131], v[224:227], v[164:167], v[116:131]
	v_add_f32_e32 v3, v160, v3
	v_add_f32_e32 v3, v161, v3
	v_add_f32_e32 v3, v162, v3
	v_add_f32_e32 v17, v163, v3
	v_cvt_pk_bf16_f32 v6, v160, v161
	v_cvt_pk_bf16_f32 v7, v162, v163
	s_mul_hi_u32 s17, s92, 0xcccccccd
	s_lshr_b32 s17, s17, 2
	s_mul_i32 s17, s17, 0x14000
	v_subrev_u32_e32 v243, s17, v214
	ds_read_b64_tr_b16 v[228:229], v243 offset:0
	ds_read_b64_tr_b16 v[230:231], v243 offset:0x800
	ds_read_b64_tr_b16 v[232:233], v243 offset:0x200
	ds_read_b64_tr_b16 v[234:235], v243 offset:0xa00
	ds_read_b64_tr_b16 v[236:237], v243 offset:0x400
	ds_read_b64_tr_b16 v[238:239], v243 offset:0xc00
	ds_read_b64_tr_b16 v[240:241], v243 offset:0x600
	ds_read_b64_tr_b16 v[242:243], v243 offset:0xe00
	s_nop 0
	v_cmp_ge_f32_e32 vcc, s38, v17
	s_cmp_eq_u64 vcc, exec
	s_cbranch_scc0 .LBB0_960
.LBB0_951:
	s_cmp_le_i32 s84, s35
	s_cbranch_scc0 .LBB0_961

.LBB0_955:
.LBB0_956:
	s_mul_hi_u32 s10, s92, 0xcccccccd
	s_lshr_b32 s10, s10, 2
	v_pk_add_f32 v[184:185], v[16:17], v[16:17] op_sel:[1,0] op_sel_hi:[0,1]
	s_mul_i32 s10, s10, 0x14000
	v_subrev_u32_e32 v3, s10, v214
	s_cmp_lg_u32 0, -1
	s_cselect_b32 s10, 0, 0
	v_add_u32_e32 v3, s10, v3
	ds_read_b64_tr_b16 v[148:149], v3 offset:0x1000
	ds_read_b64_tr_b16 v[150:151], v3 offset:0x1800
	ds_read_b64_tr_b16 v[152:153], v3 offset:0x1200
	ds_read_b64_tr_b16 v[154:155], v3 offset:0x1a00
	ds_read_b64_tr_b16 v[156:157], v3 offset:0x1400
	ds_read_b64_tr_b16 v[158:159], v3 offset:0x1c00
	ds_read_b64_tr_b16 v[160:161], v3 offset:0x1600
	ds_read_b64_tr_b16 v[162:163], v3 offset:0x1e00
	s_waitcnt lgkmcnt(8)
	s_nop 0
	v_mfma_f32_32x32x16_bf16 v[66:81], v[228:231], v[180:183], v[66:81]
	v_exp_f32_e32 v100, v100
	v_exp_f32_e32 v101, v101
	v_mfma_f32_32x32x16_bf16 v[50:65], v[232:235], v[180:183], v[50:65]
	v_exp_f32_e32 v102, v102
	v_exp_f32_e32 v103, v103
	v_mfma_f32_32x32x16_bf16 v[34:49], v[236:239], v[180:183], v[34:49]
	v_exp_f32_e32 v104, v104
	v_exp_f32_e32 v105, v105
	v_mfma_f32_32x32x16_bf16 v[18:33], v[240:243], v[180:183], v[18:33]
	v_exp_f32_e32 v106, v106
	v_exp_f32_e32 v107, v107
	ds_read_b64_tr_b16 v[132:133], v3 offset:0x2000
	ds_read_b64_tr_b16 v[134:135], v3 offset:0x2800
	ds_read_b64_tr_b16 v[136:137], v3 offset:0x2200
	ds_read_b64_tr_b16 v[138:139], v3 offset:0x2a00
	ds_read_b64_tr_b16 v[140:141], v3 offset:0x2400
	ds_read_b64_tr_b16 v[142:143], v3 offset:0x2c00
	ds_read_b64_tr_b16 v[144:145], v3 offset:0x2600
	ds_read_b64_tr_b16 v[146:147], v3 offset:0x2e00
	s_waitcnt lgkmcnt(8)
	v_mfma_f32_32x32x16_bf16 v[66:81], v[148:151], v[12:15], v[66:81]
	v_exp_f32_e32 v108, v108
	v_exp_f32_e32 v109, v109
	v_mfma_f32_32x32x16_bf16 v[50:65], v[152:155], v[12:15], v[50:65]
	v_exp_f32_e32 v110, v110
	v_exp_f32_e32 v111, v111
	v_mfma_f32_32x32x16_bf16 v[34:49], v[156:159], v[12:15], v[34:49]
	v_exp_f32_e32 v112, v112
	v_exp_f32_e32 v113, v113
	v_mfma_f32_32x32x16_bf16 v[18:33], v[160:163], v[12:15], v[18:33]
	v_exp_f32_e32 v114, v114
	v_exp_f32_e32 v115, v115
	ds_read_b64_tr_b16 v[12:13], v3 offset:0x3000
	ds_read_b64_tr_b16 v[14:15], v3 offset:0x3800
	ds_read_b64_tr_b16 v[148:149], v3 offset:0x3200
	ds_read_b64_tr_b16 v[150:151], v3 offset:0x3a00
	ds_read_b64_tr_b16 v[152:153], v3 offset:0x3400
	ds_read_b64_tr_b16 v[154:155], v3 offset:0x3c00
	ds_read_b64_tr_b16 v[156:157], v3 offset:0x3600
	ds_read_b64_tr_b16 v[158:159], v3 offset:0x3e00
	s_waitcnt lgkmcnt(8)
	v_mfma_f32_32x32x16_bf16 v[66:81], v[132:135], v[8:11], v[66:81]
	v_exp_f32_e32 v116, v116
	v_exp_f32_e32 v117, v117
	v_mfma_f32_32x32x16_bf16 v[50:65], v[136:139], v[8:11], v[50:65]
	v_exp_f32_e32 v118, v118
	v_exp_f32_e32 v119, v119
	v_mfma_f32_32x32x16_bf16 v[34:49], v[140:143], v[8:11], v[34:49]
	v_exp_f32_e32 v120, v120
	v_exp_f32_e32 v121, v121
	v_mfma_f32_32x32x16_bf16 v[18:33], v[144:147], v[8:11], v[18:33]
	v_exp_f32_e32 v122, v122
	v_exp_f32_e32 v123, v123
	s_waitcnt lgkmcnt(0)
	v_mfma_f32_32x32x16_bf16 v[66:81], v[12:15], v[4:7], v[66:81]
	v_exp_f32_e32 v124, v124
	v_exp_f32_e32 v125, v125
	v_mfma_f32_32x32x16_bf16 v[50:65], v[148:151], v[4:7], v[50:65]
	v_exp_f32_e32 v126, v126
	v_exp_f32_e32 v127, v127
	v_mfma_f32_32x32x16_bf16 v[34:49], v[152:155], v[4:7], v[34:49]
	v_exp_f32_e32 v128, v128
	v_exp_f32_e32 v129, v129
	v_mfma_f32_32x32x16_bf16 v[18:33], v[156:159], v[4:7], v[18:33]
	v_exp_f32_e32 v130, v130
	v_exp_f32_e32 v131, v131
	s_waitcnt vmcnt(0) lgkmcnt(0)
	s_barrier
	s_addk_i32 s80, 0x4000
	v_add_u32_e32 v214, 0x8000, v214
	s_add_i32 s92, s92, 2
	s_add_i32 s14, s14, 0x8000
	s_add_i32 s13, s13, 2
	v_add_u32_e32 v215, 0x8000, v215
	s_add_i32 s81, s81, 2
	s_add_i32 s15, s15, 0x8000
	s_add_i32 s12, s12, 2
	s_and_b64 vcc, exec, s[68:69]
	s_cbranch_vccnz .LBB0_962
	s_mov_b32 s10, s6
	s_mov_b32 s84, s83
	s_add_i32 s6, s84, 1
	s_cmp_ge_u32 s6, s50
	s_cbranch_scc0 .LBB0_937
	s_branch .LBB0_938
